# static s_setprio 1 for waves 4-7 during the attention phase (reset at phase end)
# speedup vs baseline: 1.0040x; 1.0040x over previous
; __device__ __forceinline__ KP kp_fresh(KP k) { asm volatile("" : "+s"(k)); return k; }
; __device__ __forceinline__ int tid_fresh(int wid) { return wid * 64 + lane_id(); }
; #define ATT_BAR() do { asm volatile("s_waitcnt lgkmcnt(0)" ::: "memory"); __builtin_amdgcn_s_barrier(); asm volatile("" ::: "memory"); } while (0)
; #define ATT_LOADK(kt_, S_) do { int grow_ = rowb + 64 * (kt_) + key_l; grow_ = grow_ < RR ? grow_ : RR - 1; \
;             kreg##S_ = *(const u32x4*)(KV + (size_t)grow_ * 2048 + h * 128 + c8 * 8); rreg##S_ = *(const u32x4*)(KR + (size_t)grow_ * 32 + (c8 & 3) * 8); } while (0)
; #define ATT_LOADV(kt_, S_) do { int g0_ = rowb + 64 * (kt_) + 2 * kp2, g1_ = g0_ + 1; g0_ = g0_ < RR ? g0_ : RR - 1; g1_ = g1_ < RR ? g1_ : RR - 1; \
;             va##S_ = *(const u32x2*)(KV + (size_t)g0_ * 2048 + h * 128 + 64 + g4 * 4); vb##S_ = *(const u32x2*)(KV + (size_t)g1_ * 2048 + h * 128 + 64 + g4 * 4); } while (0)
; #define ATT_STOREK(slot_, S_) do { LAS unsigned char* kb_ = lds + (slot_) * KBYTES; \
;             *(LAS u32x4*)(kb_ + key_l * KPT + c8 * 16) = kreg##S_; if (c8 < 4) *(LAS u32x4*)(kb_ + key_l * KPT + 128 + c8 * 16) = rreg##S_; } while (0)
; __device__ __forceinline__ void attn_phase(LAS unsigned char* lds, KP kp, int wid0) {
;     kp = kp_fresh(kp); unsigned char* ws = kp->ws;
;     const bf16* Q = (const bf16*)(ws + WS_Q); const bf16* KV = (const bf16*)(ws + WS_KV); const bf16* KR = (const bf16*)(ws + WS_KR); bf16* O = (bf16*)(ws + WS_O);
;     const int tid = tid_fresh(wid0), lane = tid & 63, wid = tid >> 6, r32 = lane & 31, hi = lane >> 5;
;     const int key_l = tid >> 3, c8 = tid & 7;
;     const int kp2 = tid >> 4, g4 = tid & 15;
;     (void)lane;
;     for (int bh = blockIdx.x; bh < NB * NHD; bh += gridDim.x) {
;         const int b = bh >> 4, h = bh & 15, rowb = b * LL;
;         bf16x8 qr[6];
;         u32x4 kregA, rregA = {}, kregB, rregB = {}; u32x2 vaA, vbA, vaB, vbB;
;     ...
;         {
;             const int qm0 = -240 + 32 * wid + r32;
;             ATT_LOADQ(qm0 < 0 ? 0 : qm0);
;             ATT_LOADK(0, A); ATT_LOADV(0, A);
;             ATT_STOREK(0, A); ATT_STOREV(0, A);
;             ATT_LOADK(0, A); ATT_LOADV(0, A);
;             ATT_BAR();
;         }
.LBB0_408:
	s_or_b64 exec, exec, s[2:3]
	v_readlane_b32 s0, v255, 3
	v_readlane_b32 s1, v255, 4
	s_mov_b64 s[2:3], s[88:89]
	s_andn2_b64 vcc, exec, s[0:1]
	s_waitcnt lgkmcnt(0)
	s_barrier
	v_mbcnt_lo_u32_b32 v1, -1, 0
	v_mbcnt_hi_u32_b32 v1, -1, v1
	s_cbranch_vccnz .LBB0_477
	s_load_dwordx2 s[0:1], s[2:3], 0x98
	s_cmpk_ge_u32 s61, 0x100
	s_cbranch_scc0 .Latt_prio_done
	s_setprio 1
.Latt_prio_done:
	v_add_u32_e32 v2, s61, v1
	v_ashrrev_i32_e32 v11, 6, v2
	v_lshlrev_b32_e32 v12, 5, v11
	v_lshlrev_b32_e32 v4, 4, v1
	v_and_b32_e32 v165, 31, v1
	s_waitcnt lgkmcnt(0)
	s_add_u32 s100, s0, 0xabb0000
	s_addc_u32 s101, s1, 0
	s_add_u32 s48, s0, 0xadb4000
	v_add_u32_e32 v195, 0xffffff10, v12
	v_and_b32_e32 v4, 48, v4
	v_mov_b32_e32 v239, v4
	v_mov_b32_e32 v5, v0
	v_ashrrev_i32_e32 v194, 3, v2
	v_ashrrev_i32_e32 v3, 4, v2
	s_addc_u32 s49, s1, 0
	v_and_b32_e32 v7, 7, v1
	v_add_u32_e32 v2, v195, v165
	v_lshl_add_u64 v[4:5], s[0:1], 0, v[4:5]
	s_mov_b64 s[2:3], 0xabb0000
	s_add_u32 s60, s0, 0x10e74000
	v_max_i32_e32 v196, 0, v2
	v_lshlrev_b32_e32 v2, 3, v7
	v_lshl_add_u64 v[166:167], v[4:5], 0, s[2:3]
	v_lshlrev_b32_e32 v6, 4, v7
	v_mov_b32_e32 v238, v6
	v_cmp_gt_u32_e64 s[2:3], 4, v7
	v_mov_b32_e32 v7, v0
	s_addc_u32 s61, s1, 0
	s_movk_i32 s5, 0xd0
	v_lshl_add_u64 v[8:9], s[0:1], 0, v[6:7]
	s_mov_b64 s[0:1], 0x5300000
	v_lshl_add_u64 v[168:169], v[8:9], 0, s[0:1]
	v_mad_u32_u24 v198, v165, s5, 0
	s_movk_i32 s1, 0xffb8
	v_mad_i32_i24 v200, v165, s1, v198
	s_movk_i32 s0, 0x48
	v_lshl_add_u64 v[170:171], s[60:61], 0, v[6:7]
	v_mad_u32_u24 v202, v165, s0, v200
	v_or_b32_e32 v7, v165, v12
	s_movk_i32 s0, 0x1200
	v_lshlrev_b32_e32 v4, 2, v1
	v_add_u32_e32 v204, 16, v7
	v_mul_lo_u32 v7, v11, s0
	v_bfe_u32 v10, v1, 5, 1
	v_and_b32_e32 v4, 60, v4
	v_mul_lo_u32 v5, v194, s5
	s_movk_i32 s4, 0x88
	v_add_u32_e32 v7, 0, v7
	s_movk_i32 s0, 0x90
	v_bfe_u32 v205, v1, 3, 3
	v_lshlrev_b32_e32 v164, 3, v10
	v_lshlrev_b32_e32 v197, 1, v3
	v_add_u32_e32 v5, 0, v5
	v_mad_u32_u24 v13, v4, s4, 0
	v_lshlrev_b32_e32 v3, 2, v3
	v_mad_u32_u24 v8, v165, s0, v7
	v_add_u32_e32 v1, v7, v6
	v_mul_u32_u24_e32 v7, 0x90, v205
	v_lshlrev_b32_e32 v199, 4, v10
	v_lshlrev_b32_e32 v201, 2, v10
	v_mad_i32_i24 v203, v165, s1, v202
	v_or_b32_e32 v206, 8, v205
	v_or_b32_e32 v207, 16, v205
	v_or_b32_e32 v208, 24, v205
	v_lshlrev_b32_e32 v172, 1, v2
	v_lshlrev_b32_e32 v174, 1, v4
	v_add_u32_e32 v209, v8, v164
	v_add_u32_e32 v210, v5, v6
	v_add_u32_e32 v211, v13, v3
	v_add_u32_e32 v212, v1, v7
	v_add_u32_e32 v240, v198, v199
	v_add_u32_e32 v241, v202, v199
	v_add_u32_e32 v250, v200, v164
	v_add_u32_e32 v251, 0x9800, v250
	v_add_u32_e32 v250, 0x8800, v250
	v_add_u32_e32 v252, v203, v164
	v_add_u32_e32 v253, 0x7800, v252
	v_add_u32_e32 v252, 0x6800, v252
	v_add_u32_e32 v254, 0x8800, v211
	s_mov_b32 s94, 0x5040100
	s_mov_b32 s95, 0x7060302
	s_mov_b32 s0, s33
	s_branch .LBB0_411

; #define GSYNC() gsync(kp0, lds, wid0)
; __device__ __forceinline__ void xcd_barrier(const XcdBarrier& b, int tid) {
;     asm volatile("s_waitcnt vmcnt(0)" ::: "memory");
;     __syncthreads();
;     if (tid == 0) {
;         unsigned* bar = b.bar;
;         __builtin_amdgcn_s_waitcnt(0);
;         unsigned nloc = b.st[0], nx = b.st[1];
;         if (nloc == 0u) { xcd_barrier_complete(bar, b.x, nloc, nx); b.st[0] = nloc; b.st[1] = nx; }
; __global__ void __launch_bounds__(512, 2) hybrid_fwd(Params p_unused) {
;     ...
;             att::attn_phase(lds, kp0, wid0);
;             GSYNC();
.LBB0_477:
	s_setprio 0
	s_mov_b64 s[4:5], s[88:89]
	s_getreg_b32 s0, hwreg(HW_REG_XCC_ID, 0, 4)
	v_mbcnt_lo_u32_b32 v1, -1, 0
	v_mbcnt_hi_u32_b32 v1, -1, v1
	s_waitcnt vmcnt(0)
	v_readlane_b32 s1, v255, 0
	s_waitcnt lgkmcnt(0)
	s_barrier
	v_cmp_eq_u32_e32 vcc, s1, v1
	s_and_saveexec_b64 s[2:3], vcc
	s_cbranch_execz .LBB0_529
	v_readlane_b32 s1, v255, 32
	s_load_dwordx2 s[4:5], s[4:5], 0x98
	s_waitcnt vmcnt(0) expcnt(0) lgkmcnt(0)
	v_mov_b32_e32 v1, s1
	ds_read_b32 v3, v1
	v_readlane_b32 s1, v255, 33
	s_and_b32 s0, s0, 15
	s_waitcnt lgkmcnt(0)
	v_cmp_ne_u32_e32 vcc, 0, v3
	v_mov_b32_e32 v1, s1
	ds_read_b32 v2, v1
	s_cbranch_vccnz .LBB0_493
	s_add_u32 s6, s4, 0x1000
	s_addc_u32 s7, s5, 0
	s_add_u32 s8, s4, 0x1100
	s_addc_u32 s9, s5, 0
	s_add_u32 s10, s4, 0x1200
	s_addc_u32 s11, s5, 0
	s_add_u32 s12, s4, 0x1300
	s_addc_u32 s13, s5, 0
	s_mov_b32 s1, 1
	s_branch .LBB0_481
